# grid barrier flattened: XCD-last adds to TOP, every workgroup polls TOP target (no TOPGEN/XGEN hops); on v7+dpp fusion
# speedup vs baseline: 1.0062x; 1.0014x over previous
; #define LAS __attribute__((address_space(3)))
; __device__ __forceinline__ int otid(int wv) { int ln; asm volatile("v_mbcnt_lo_u32_b32 %0, -1, 0\n\tv_mbcnt_hi_u32_b32 %0, -1, %0" : "=v"(ln)); return wv * 64 + ln; }
; __device__ __forceinline__ unsigned xb_add(unsigned* p, unsigned v) { return __hip_atomic_fetch_add(p, v, __ATOMIC_RELAXED, __HIP_MEMORY_SCOPE_AGENT); }
; __device__ __forceinline__ unsigned xb_xcc_id() { return (unsigned)__builtin_amdgcn_s_getreg((3 << 11) | 20) & 0xFu; }
; __global__ void __launch_bounds__(512, 2) hybrid_fwd(Params p_unused) {
;     extern __shared__ __attribute__((aligned(16))) unsigned char smem[];
;     LAS unsigned char* lds = (LAS unsigned char*)smem;
;     const int wv = __builtin_amdgcn_readfirstlane((int)(threadIdx.x >> 6));
;     const int G = gridDim.x, c = blockIdx.x;
;     { volatile LAS unsigned* st = (volatile LAS unsigned*)(lds + QWORD_OFF + 4); const Params pb = ldp();
;       if (otid(wv) == 0) { st[0] = 0u; st[1] = 0u; (void)xb_add((unsigned*)(pb.ws + OFF_BAR) + XB_XCNT(xb_xcc_id()), 1u); }
;       __syncthreads(); }
_Z10hybrid_fwd6Params:
	s_mov_b64 s[90:91], s[0:1]
	s_mov_b32 s100, 0
	s_load_dword s44, s[90:91], 0xb0
	v_readfirstlane_b32 s0, v0
	s_and_b32 s89, s0, 0xffffffc0
	s_mov_b64 s[6:7], s[90:91]
	s_sub_i32 s1, 0, s89
	s_mov_b32 s96, s2
	v_mbcnt_lo_u32_b32 v0, -1, 0
	v_mbcnt_hi_u32_b32 v0, -1, v0
	v_writelane_b32 v253, s1, 0
	v_cmp_eq_u32_e32 vcc, s1, v0
	s_and_saveexec_b64 s[4:5], vcc
	s_cbranch_execz .LBB0_3
	s_add_i32 s1, 0, 0x23ff4
	v_mov_b32_e32 v0, 0
	v_mov_b32_e32 v1, s1
	s_add_i32 s1, 0, 0x23ff8
	s_mov_b64 s[8:9], exec
	ds_write_b32 v1, v0
	v_mov_b32_e32 v1, s1
	ds_write_b32 v1, v0
	v_mbcnt_lo_u32_b32 v0, s8, 0
	v_mbcnt_hi_u32_b32 v0, s9, v0
	v_cmp_eq_u32_e32 vcc, 0, v0
	s_getreg_b32 s1, hwreg(HW_REG_XCC_ID, 0, 4)
	s_and_b64 s[2:3], exec, vcc
	s_mov_b64 exec, s[2:3]
	s_cbranch_execz .LBB0_3
	s_load_dwordx2 s[2:3], s[6:7], 0xa8
	s_lshl_b32 s1, s1, 8
	s_and_b32 s1, s1, 0xf00
	v_mov_b32_e32 v0, 0xfab9000
	s_waitcnt lgkmcnt(0)
	s_add_u32 s2, s2, s1
	s_addc_u32 s3, s3, 0
	s_bcnt1_i32_b64 s1, s[8:9]
	v_mov_b32_e32 v1, s1
	global_atomic_add v0, v1, s[2:3] offset:3328

; __device__ __forceinline__ unsigned xb_ld(unsigned* p)              { return __hip_atomic_load(p, __ATOMIC_RELAXED, __HIP_MEMORY_SCOPE_AGENT); }
; __device__ __forceinline__ unsigned xb_add(unsigned* p, unsigned v) { return __hip_atomic_fetch_add(p, v, __ATOMIC_RELAXED, __HIP_MEMORY_SCOPE_AGENT); }
; #define XB_SPIN(cond, bar) do { unsigned _sp = 0; while (cond) { __builtin_amdgcn_s_sleep(1); \
;     if ((++_sp & 255u) == 0u) { if (xb_ld(&(bar)[XB_TMO])) break; if (_sp > XB_SPIN_CAP) { atomicAdd(&(bar)[XB_TMO], 1u); break; } } } } while (0)
; __device__ __forceinline__ void grid_bar(int wv, unsigned* bar, volatile LAS unsigned* st) {
;     ...
;         const unsigned old = xb_add(&bar[XB_XSUB(x)], 1u);
;         const unsigned gen = old / nloc;
;         if (old + 1u == (gen + 1u) * nloc) {
;             __builtin_amdgcn_fence(__ATOMIC_RELEASE, "agent");
;             asm volatile("s_waitcnt vmcnt(0)" ::: "memory");
;             const unsigned og = xb_add(&bar[XB_TOP], 1u);
;             const unsigned tg = og / nx;
;             if (og + 1u == (tg + 1u) * nx) xb_add(&bar[XB_TOPGEN], 1u);
;             else XB_SPIN(xb_ld(&bar[XB_TOPGEN]) == tg, bar);
;             __builtin_amdgcn_fence(__ATOMIC_ACQUIRE, "agent");
;             xb_add(&bar[XB_XGEN(x)], 1u);
;             asm volatile("s_waitcnt vmcnt(0)" ::: "memory");
;         } else {
;             XB_SPIN(xb_ld(&bar[XB_XGEN(x)]) == gen, bar);
;             __builtin_amdgcn_fence(__ATOMIC_ACQUIRE, "agent");
;             asm volatile("s_waitcnt vmcnt(0)" ::: "memory");
;         }
.LBB0_47:
	s_or_b64 exec, exec, s[12:13]
	s_waitcnt vmcnt(0) lgkmcnt(0)
	v_readfirstlane_b32 s1, v3
	v_readfirstlane_b32 s2, v2
	s_add_i32 s100, s100, 1
	s_add_i32 s1, s1, 1
	s_mul_i32 s2, s2, s100
	s_add_u32 s10, s6, 0xfabcd00
	s_addc_u32 s11, s7, 0
	v_readfirstlane_b32 s101, v0
	v_mov_b32_e32 v4, 0
	s_cmp_lg_u32 s1, s2
	s_mul_i32 s2, s101, s100
	s_cbranch_scc1 .Lgb_spin_0
	buffer_wbl2 sc1
	v_mov_b32_e32 v5, 1
	s_waitcnt vmcnt(0)
	global_atomic_add v4, v5, s[10:11]
.Lgb_spin_0:
	s_mov_b32 s1, 0
.Lgb_loop_0:
	global_load_dword v5, v4, s[10:11] sc1
	s_waitcnt vmcnt(0)
	v_readfirstlane_b32 s101, v5
	s_cmp_ge_u32 s101, s2
	s_cbranch_scc1 .Lgb_done_0
	s_sleep 1
	s_add_i32 s1, s1, 1
	s_bitcmp1_b32 s1, 18
	s_cbranch_scc0 .Lgb_loop_0
.Lgb_done_0:
	buffer_inv sc1
	s_waitcnt vmcnt(0)

; __device__ __forceinline__ unsigned xb_ld(unsigned* p)              { return __hip_atomic_load(p, __ATOMIC_RELAXED, __HIP_MEMORY_SCOPE_AGENT); }
; __device__ __forceinline__ unsigned xb_add(unsigned* p, unsigned v) { return __hip_atomic_fetch_add(p, v, __ATOMIC_RELAXED, __HIP_MEMORY_SCOPE_AGENT); }
; #define XB_SPIN(cond, bar) do { unsigned _sp = 0; while (cond) { __builtin_amdgcn_s_sleep(1); \
;     if ((++_sp & 255u) == 0u) { if (xb_ld(&(bar)[XB_TMO])) break; if (_sp > XB_SPIN_CAP) { atomicAdd(&(bar)[XB_TMO], 1u); break; } } } } while (0)
; __device__ __forceinline__ void grid_bar(int wv, unsigned* bar, volatile LAS unsigned* st) {
;     ...
;         const unsigned old = xb_add(&bar[XB_XSUB(x)], 1u);
;         const unsigned gen = old / nloc;
;         if (old + 1u == (gen + 1u) * nloc) {
;             __builtin_amdgcn_fence(__ATOMIC_RELEASE, "agent");
;             asm volatile("s_waitcnt vmcnt(0)" ::: "memory");
;             const unsigned og = xb_add(&bar[XB_TOP], 1u);
;             const unsigned tg = og / nx;
;             if (og + 1u == (tg + 1u) * nx) xb_add(&bar[XB_TOPGEN], 1u);
;             else XB_SPIN(xb_ld(&bar[XB_TOPGEN]) == tg, bar);
;             __builtin_amdgcn_fence(__ATOMIC_ACQUIRE, "agent");
;             xb_add(&bar[XB_XGEN(x)], 1u);
;             asm volatile("s_waitcnt vmcnt(0)" ::: "memory");
;         } else {
;             XB_SPIN(xb_ld(&bar[XB_XGEN(x)]) == gen, bar);
;             __builtin_amdgcn_fence(__ATOMIC_ACQUIRE, "agent");
;             asm volatile("s_waitcnt vmcnt(0)" ::: "memory");
;         }
.LBB0_331:
	s_or_b64 exec, exec, s[12:13]
	s_waitcnt vmcnt(0) lgkmcnt(0)
	v_readfirstlane_b32 s0, v4
	v_readfirstlane_b32 s1, v3
	s_add_i32 s100, s100, 1
	s_add_i32 s0, s0, 1
	s_mul_i32 s1, s1, s100
	s_add_u32 s4, s8, 0xfabcd00
	s_addc_u32 s5, s9, 0
	v_readfirstlane_b32 s101, v0
	v_mov_b32_e32 v5, 0
	s_cmp_lg_u32 s0, s1
	s_mul_i32 s1, s101, s100
	s_cbranch_scc1 .Lgb_spin_1
	buffer_wbl2 sc1
	v_mov_b32_e32 v6, 1
	s_waitcnt vmcnt(0)
	global_atomic_add v5, v6, s[4:5]
.Lgb_spin_1:
	s_mov_b32 s0, 0
.Lgb_loop_1:
	global_load_dword v6, v5, s[4:5] sc1
	s_waitcnt vmcnt(0)
	v_readfirstlane_b32 s101, v6
	s_cmp_ge_u32 s101, s1
	s_cbranch_scc1 .Lgb_done_1
	s_sleep 1
	s_add_i32 s0, s0, 1
	s_bitcmp1_b32 s0, 18
	s_cbranch_scc0 .Lgb_loop_1

; __device__ __forceinline__ unsigned xb_ld(unsigned* p)              { return __hip_atomic_load(p, __ATOMIC_RELAXED, __HIP_MEMORY_SCOPE_AGENT); }
; __device__ __forceinline__ unsigned xb_add(unsigned* p, unsigned v) { return __hip_atomic_fetch_add(p, v, __ATOMIC_RELAXED, __HIP_MEMORY_SCOPE_AGENT); }
; #define XB_SPIN(cond, bar) do { unsigned _sp = 0; while (cond) { __builtin_amdgcn_s_sleep(1); \
;     if ((++_sp & 255u) == 0u) { if (xb_ld(&(bar)[XB_TMO])) break; if (_sp > XB_SPIN_CAP) { atomicAdd(&(bar)[XB_TMO], 1u); break; } } } } while (0)
; __device__ __forceinline__ void grid_bar(int wv, unsigned* bar, volatile LAS unsigned* st) {
;     ...
;         const unsigned old = xb_add(&bar[XB_XSUB(x)], 1u);
;         const unsigned gen = old / nloc;
;         if (old + 1u == (gen + 1u) * nloc) {
;             __builtin_amdgcn_fence(__ATOMIC_RELEASE, "agent");
;             asm volatile("s_waitcnt vmcnt(0)" ::: "memory");
;             const unsigned og = xb_add(&bar[XB_TOP], 1u);
;             const unsigned tg = og / nx;
;             if (og + 1u == (tg + 1u) * nx) xb_add(&bar[XB_TOPGEN], 1u);
;             else XB_SPIN(xb_ld(&bar[XB_TOPGEN]) == tg, bar);
;             __builtin_amdgcn_fence(__ATOMIC_ACQUIRE, "agent");
;             xb_add(&bar[XB_XGEN(x)], 1u);
;             asm volatile("s_waitcnt vmcnt(0)" ::: "memory");
;         } else {
;             XB_SPIN(xb_ld(&bar[XB_XGEN(x)]) == gen, bar);
;             __builtin_amdgcn_fence(__ATOMIC_ACQUIRE, "agent");
;             asm volatile("s_waitcnt vmcnt(0)" ::: "memory");
;         }
.LBB0_552:
	s_or_b64 exec, exec, s[12:13]
	s_waitcnt vmcnt(0) lgkmcnt(0)
	v_readfirstlane_b32 s0, v4
	v_readfirstlane_b32 s1, v3
	s_add_i32 s100, s100, 1
	s_add_i32 s0, s0, 1
	s_mul_i32 s1, s1, s100
	s_add_u32 s4, s8, 0xfabcd00
	s_addc_u32 s5, s9, 0
	v_readfirstlane_b32 s101, v2
	v_mov_b32_e32 v5, 0
	s_cmp_lg_u32 s0, s1
	s_mul_i32 s1, s101, s100
	s_cbranch_scc1 .Lgb_spin_2
	buffer_wbl2 sc1
	v_mov_b32_e32 v6, 1
	s_waitcnt vmcnt(0)
	global_atomic_add v5, v6, s[4:5]

; __device__ __forceinline__ unsigned xb_ld(unsigned* p)              { return __hip_atomic_load(p, __ATOMIC_RELAXED, __HIP_MEMORY_SCOPE_AGENT); }
; #define XB_SPIN(cond, bar) do { unsigned _sp = 0; while (cond) { __builtin_amdgcn_s_sleep(1); \
;     if ((++_sp & 255u) == 0u) { if (xb_ld(&(bar)[XB_TMO])) break; if (_sp > XB_SPIN_CAP) { atomicAdd(&(bar)[XB_TMO], 1u); break; } } } } while (0)
; __device__ __forceinline__ void grid_bar(int wv, unsigned* bar, volatile LAS unsigned* st) {
;     ...
;             XB_SPIN(xb_ld(&bar[XB_XGEN(x)]) == gen, bar);
;             __builtin_amdgcn_fence(__ATOMIC_ACQUIRE, "agent");
;             asm volatile("s_waitcnt vmcnt(0)" ::: "memory");
.Lgb_done_2:
	buffer_inv sc1
	s_waitcnt vmcnt(0)
	s_branch .Lgb_end_2

; __device__ __forceinline__ float bflo(unsigned w) { return __uint_as_float(w << 16); }
; __device__ __forceinline__ float bfhi(unsigned w) { return __uint_as_float(w & 0xffff0000u); }
; __device__ __forceinline__ int otid(int wv) { int ln; asm volatile("v_mbcnt_lo_u32_b32 %0, -1, 0\n\tv_mbcnt_hi_u32_b32 %0, -1, %0" : "=v"(ln)); return wv * 64 + ln; }
; __device__ __forceinline__ float shx(float v, int m, int lane) { return __int_as_float(__builtin_amdgcn_ds_bpermute((lane ^ m) << 2, __float_as_int(v))); }
; __device__ __forceinline__ void fourier_mid_row(int wv, const Params& p) {
;     const int tid = otid(wv), lane = tid & 63, gw = blockIdx.x * 8 + (tid >> 6), nw = gridDim.x * 8;
;     const bf16_t* TLAT = (const bf16_t*)(p.ws + OFF_TLAT); bf16_t* PQ = (bf16_t*)(p.ws + OFF_PQ);
;     for (int pr = gw; pr < 2048; pr += nw) { const int bt = pr >> 8, ch = pr & 255;
;         const bf16_t* src = TLAT + ((size_t)bt * 1024 + ch) * 2048 + lane * 32; float acc = 0.f;
; #pragma unroll
;         for (int j = 0; j < 4; ++j) { const u32x4 w = *(const u32x4*)(src + j * 8);
;             acc += (bflo(w.x) - bfhi(w.x)) + (bflo(w.y) - bfhi(w.y)) + (bflo(w.z) - bfhi(w.z)) + (bflo(w.w) - bfhi(w.w)); }
; #pragma unroll
;         for (int o = 32; o >= 1; o >>= 1) acc += shx(acc, o, lane);
.Lgb_end_2:
.LBB0_587:
	s_or_b64 exec, exec, s[6:7]
	s_mov_b64 s[4:5], s[90:91]
	s_waitcnt lgkmcnt(0)
	s_barrier
	v_mbcnt_lo_u32_b32 v0, -1, 0
	v_mbcnt_hi_u32_b32 v0, -1, v0
	v_readlane_b32 s0, v254, 30
	v_add_u32_e32 v2, s89, v0
	v_ashrrev_i32_e32 v2, 6, v2
	v_add_u32_e32 v6, s0, v2
	s_movk_i32 s0, 0x800
	v_cmp_gt_i32_e32 vcc, s0, v6
	s_and_saveexec_b64 s[6:7], vcc
	s_cbranch_execz .LBB0_592
	s_load_dwordx2 s[0:1], s[4:5], 0xa8
	v_and_b32_e32 v2, 63, v0
	v_lshlrev_b32_e32 v0, 5, v2
	v_cmp_eq_u32_e64 s[10:11], 0, v2
	v_lshlrev_b32_e32 v2, 2, v2
	s_waitcnt lgkmcnt(0)
	s_add_u32 s8, s0, 0x6320000
	s_addc_u32 s9, s1, 0
	s_add_u32 s12, s0, 0x8720000
	s_addc_u32 s13, s1, 0
	v_xor_b32_e32 v7, 0x80, v2
	v_xor_b32_e32 v8, 64, v2
	v_xor_b32_e32 v9, 32, v2
	v_xor_b32_e32 v10, 16, v2
	v_xor_b32_e32 v11, 8, v2
	v_xor_b32_e32 v12, 4, v2
	s_mov_b64 s[14:15], 0
	v_lshlrev_b32_e32 v2, 1, v0
	s_branch .LBB0_590

; __device__ __forceinline__ unsigned xb_ld(unsigned* p)              { return __hip_atomic_load(p, __ATOMIC_RELAXED, __HIP_MEMORY_SCOPE_AGENT); }
; __device__ __forceinline__ unsigned xb_add(unsigned* p, unsigned v) { return __hip_atomic_fetch_add(p, v, __ATOMIC_RELAXED, __HIP_MEMORY_SCOPE_AGENT); }
; #define XB_SPIN(cond, bar) do { unsigned _sp = 0; while (cond) { __builtin_amdgcn_s_sleep(1); \
;     if ((++_sp & 255u) == 0u) { if (xb_ld(&(bar)[XB_TMO])) break; if (_sp > XB_SPIN_CAP) { atomicAdd(&(bar)[XB_TMO], 1u); break; } } } } while (0)
; __device__ __forceinline__ void grid_bar(int wv, unsigned* bar, volatile LAS unsigned* st) {
;     ...
;         const unsigned old = xb_add(&bar[XB_XSUB(x)], 1u);
;         const unsigned gen = old / nloc;
;         if (old + 1u == (gen + 1u) * nloc) {
;             __builtin_amdgcn_fence(__ATOMIC_RELEASE, "agent");
;             asm volatile("s_waitcnt vmcnt(0)" ::: "memory");
;             const unsigned og = xb_add(&bar[XB_TOP], 1u);
;             const unsigned tg = og / nx;
;             if (og + 1u == (tg + 1u) * nx) xb_add(&bar[XB_TOPGEN], 1u);
;             else XB_SPIN(xb_ld(&bar[XB_TOPGEN]) == tg, bar);
;             __builtin_amdgcn_fence(__ATOMIC_ACQUIRE, "agent");
;             xb_add(&bar[XB_XGEN(x)], 1u);
;             asm volatile("s_waitcnt vmcnt(0)" ::: "memory");
;         } else {
;             XB_SPIN(xb_ld(&bar[XB_XGEN(x)]) == gen, bar);
;             __builtin_amdgcn_fence(__ATOMIC_ACQUIRE, "agent");
;             asm volatile("s_waitcnt vmcnt(0)" ::: "memory");
;         }
.LBB0_1181:
	s_or_b64 exec, exec, s[16:17]
	s_waitcnt vmcnt(0) lgkmcnt(0)
	v_readfirstlane_b32 s0, v4
	v_readfirstlane_b32 s1, v3
	s_add_i32 s100, s100, 1
	s_add_i32 s0, s0, 1
	s_mul_i32 s1, s1, s100
	s_add_u32 s4, s8, 0xfabcd00
	s_addc_u32 s5, s9, 0
	v_readfirstlane_b32 s101, v2
	v_mov_b32_e32 v5, 0
	s_cmp_lg_u32 s0, s1
	s_mul_i32 s1, s101, s100
	s_cbranch_scc1 .Lgb_spin_6
	buffer_wbl2 sc1
	v_mov_b32_e32 v6, 1
	s_waitcnt vmcnt(0)
	global_atomic_add v5, v6, s[4:5]

; __device__ __forceinline__ unsigned xb_ld(unsigned* p)              { return __hip_atomic_load(p, __ATOMIC_RELAXED, __HIP_MEMORY_SCOPE_AGENT); }
; __device__ __forceinline__ unsigned xb_add(unsigned* p, unsigned v) { return __hip_atomic_fetch_add(p, v, __ATOMIC_RELAXED, __HIP_MEMORY_SCOPE_AGENT); }
; #define XB_SPIN(cond, bar) do { unsigned _sp = 0; while (cond) { __builtin_amdgcn_s_sleep(1); \
;     if ((++_sp & 255u) == 0u) { if (xb_ld(&(bar)[XB_TMO])) break; if (_sp > XB_SPIN_CAP) { atomicAdd(&(bar)[XB_TMO], 1u); break; } } } } while (0)
; __device__ __forceinline__ void grid_bar(int wv, unsigned* bar, volatile LAS unsigned* st) {
;     ...
;         const unsigned old = xb_add(&bar[XB_XSUB(x)], 1u);
;         const unsigned gen = old / nloc;
;         if (old + 1u == (gen + 1u) * nloc) {
;             __builtin_amdgcn_fence(__ATOMIC_RELEASE, "agent");
;             asm volatile("s_waitcnt vmcnt(0)" ::: "memory");
;             const unsigned og = xb_add(&bar[XB_TOP], 1u);
;             const unsigned tg = og / nx;
;             if (og + 1u == (tg + 1u) * nx) xb_add(&bar[XB_TOPGEN], 1u);
;             else XB_SPIN(xb_ld(&bar[XB_TOPGEN]) == tg, bar);
;             __builtin_amdgcn_fence(__ATOMIC_ACQUIRE, "agent");
;             xb_add(&bar[XB_XGEN(x)], 1u);
;             asm volatile("s_waitcnt vmcnt(0)" ::: "memory");
;         } else {
;             XB_SPIN(xb_ld(&bar[XB_XGEN(x)]) == gen, bar);
;             __builtin_amdgcn_fence(__ATOMIC_ACQUIRE, "agent");
;             asm volatile("s_waitcnt vmcnt(0)" ::: "memory");
;         }
.Lgb_done_9:
	buffer_inv sc1
	s_waitcnt vmcnt(0)
	s_getpc_b64 s[98:99]
